# v14_anysel
# speedup vs baseline: 1.0704x; 1.0087x over previous
; DEVI void moba_item(const Params& p, int l, int item) {
;     ...
;   if (tid < 128) {
;     float v1 = -INFINITY, v2 = -INFINITY, v3 = -INFINITY;
;     int i1 = -1, i2 = -1, i3 = -1;
;     for (int blk = 0; blk < qblk; ++blk) {
;       float g = gate[tid * 17 + blk];
;       if (g > v1 || i1 < 0) { v3 = v2; i3 = i2; v2 = v1; i2 = i1; v1 = g; i1 = blk; }
;       else if (g > v2 || i2 < 0) { v3 = v2; i3 = i2; v2 = g; i2 = blk; }
;       else if (g > v3 || i3 < 0) { v3 = g; i3 = blk; }
;     }
;     unsigned mask = 0u;
;     if (i1 >= 0) mask |= 1u << i1;
;     if (i2 >= 0) mask |= 1u << i2;
;     if (i3 >= 0) mask |= 1u << i3;
;     selm[tid] = mask;
;     atomicOr(&selm[128], mask);
;   }
.Lmy_gd_done:
	v_cmp_gt_u32_e32 vcc, s67, v48
	s_waitcnt lgkmcnt(0)
	s_barrier
	s_and_saveexec_b64 s[2:3], vcc
	s_cbranch_execz .LBB0_653
	v_mov_b32_e32 v37, 0
	v_mov_b32_e32 v38, 0
	v_mov_b32_e32 v39, 0
	s_cmp_eq_u32 s28, 0
	s_cbranch_scc1 .Lmy_t3_done
	v_mov_b32_e32 v32, s96
	v_mad_u32_u24 v32, v48, s74, v32
	ds_read2_b32 v[56:57], v32 offset1:1
	ds_read2_b32 v[58:59], v32 offset0:2 offset1:3
	ds_read2_b32 v[60:61], v32 offset0:4 offset1:5
	ds_read2_b32 v[62:63], v32 offset0:6 offset1:7
	ds_read2_b32 v[64:65], v32 offset0:8 offset1:9
	ds_read2_b32 v[66:67], v32 offset0:10 offset1:11
	ds_read2_b32 v[68:69], v32 offset0:12 offset1:13
	ds_read2_b32 v[70:71], v32 offset0:14 offset1:15
	v_mov_b32_e32 v34, 0xff800000
	v_mov_b32_e32 v35, 0xff800000
	v_mov_b32_e32 v36, 0xff800000
	s_waitcnt lgkmcnt(7)
	v_mov_b32_e32 v44, 1
	v_cmp_gt_f32_e64 s[8:9], v56, v36
	v_cmp_gt_f32_e64 s[6:7], v56, v35
	v_cmp_gt_f32_e32 vcc, v56, v34
	v_cndmask_b32_e64 v36, v36, v56, s[8:9]
	v_cndmask_b32_e64 v39, v39, v44, s[8:9]
	v_cndmask_b32_e64 v36, v36, v35, s[6:7]
	v_cndmask_b32_e64 v39, v39, v38, s[6:7]
	v_cndmask_b32_e64 v35, v35, v56, s[6:7]
	v_cndmask_b32_e64 v38, v38, v44, s[6:7]
	v_cndmask_b32_e32 v35, v35, v34, vcc
	v_cndmask_b32_e32 v38, v38, v37, vcc
	v_cndmask_b32_e32 v34, v34, v56, vcc
	v_cndmask_b32_e32 v37, v37, v44, vcc
	s_cmp_le_u32 s28, 1
	s_cbranch_scc1 .Lmy_t3_done
	v_mov_b32_e32 v44, 2
	v_cmp_gt_f32_e64 s[8:9], v57, v36
	v_cmp_gt_f32_e64 s[6:7], v57, v35
	v_cmp_gt_f32_e32 vcc, v57, v34
	v_cndmask_b32_e64 v36, v36, v57, s[8:9]
	v_cndmask_b32_e64 v39, v39, v44, s[8:9]
	v_cndmask_b32_e64 v36, v36, v35, s[6:7]
	v_cndmask_b32_e64 v39, v39, v38, s[6:7]
	v_cndmask_b32_e64 v35, v35, v57, s[6:7]
	v_cndmask_b32_e64 v38, v38, v44, s[6:7]
	v_cndmask_b32_e32 v35, v35, v34, vcc
	v_cndmask_b32_e32 v38, v38, v37, vcc
	v_cndmask_b32_e32 v34, v34, v57, vcc
	v_cndmask_b32_e32 v37, v37, v44, vcc
	s_cmp_le_u32 s28, 2
	s_cbranch_scc1 .Lmy_t3_done
	s_waitcnt lgkmcnt(6)
	v_mov_b32_e32 v44, 4
	v_cmp_gt_f32_e64 s[8:9], v58, v36
	v_cmp_gt_f32_e64 s[6:7], v58, v35
	v_cmp_gt_f32_e32 vcc, v58, v34
	v_cndmask_b32_e64 v36, v36, v58, s[8:9]
	v_cndmask_b32_e64 v39, v39, v44, s[8:9]
	v_cndmask_b32_e64 v36, v36, v35, s[6:7]
	v_cndmask_b32_e64 v39, v39, v38, s[6:7]
	v_cndmask_b32_e64 v35, v35, v58, s[6:7]
	v_cndmask_b32_e64 v38, v38, v44, s[6:7]
	v_cndmask_b32_e32 v35, v35, v34, vcc
	v_cndmask_b32_e32 v38, v38, v37, vcc
	v_cndmask_b32_e32 v34, v34, v58, vcc
	v_cndmask_b32_e32 v37, v37, v44, vcc
	s_cmp_le_u32 s28, 3
	s_cbranch_scc1 .Lmy_t3_done
	v_mov_b32_e32 v44, 8
	v_cmp_gt_f32_e64 s[8:9], v59, v36
	v_cmp_gt_f32_e64 s[6:7], v59, v35
	v_cmp_gt_f32_e32 vcc, v59, v34
	v_cndmask_b32_e64 v36, v36, v59, s[8:9]
	v_cndmask_b32_e64 v39, v39, v44, s[8:9]
	v_cndmask_b32_e64 v36, v36, v35, s[6:7]
	v_cndmask_b32_e64 v39, v39, v38, s[6:7]
	v_cndmask_b32_e64 v35, v35, v59, s[6:7]
	v_cndmask_b32_e64 v38, v38, v44, s[6:7]
	v_cndmask_b32_e32 v35, v35, v34, vcc
	v_cndmask_b32_e32 v38, v38, v37, vcc
	v_cndmask_b32_e32 v34, v34, v59, vcc
	v_cndmask_b32_e32 v37, v37, v44, vcc
	s_cmp_le_u32 s28, 4
	s_cbranch_scc1 .Lmy_t3_done
	s_waitcnt lgkmcnt(5)
	v_mov_b32_e32 v44, 16
	v_cmp_gt_f32_e64 s[8:9], v60, v36
	v_cmp_gt_f32_e64 s[6:7], v60, v35
	v_cmp_gt_f32_e32 vcc, v60, v34
	v_cndmask_b32_e64 v36, v36, v60, s[8:9]
	v_cndmask_b32_e64 v39, v39, v44, s[8:9]
	v_cndmask_b32_e64 v36, v36, v35, s[6:7]
	v_cndmask_b32_e64 v39, v39, v38, s[6:7]
	v_cndmask_b32_e64 v35, v35, v60, s[6:7]
	v_cndmask_b32_e64 v38, v38, v44, s[6:7]
	v_cndmask_b32_e32 v35, v35, v34, vcc
	v_cndmask_b32_e32 v38, v38, v37, vcc
	v_cndmask_b32_e32 v34, v34, v60, vcc
	v_cndmask_b32_e32 v37, v37, v44, vcc
	s_cmp_le_u32 s28, 5
	s_cbranch_scc1 .Lmy_t3_done
	v_mov_b32_e32 v44, 32
	v_cmp_gt_f32_e64 s[8:9], v61, v36
	v_cmp_gt_f32_e64 s[6:7], v61, v35
	v_cmp_gt_f32_e32 vcc, v61, v34
	v_cndmask_b32_e64 v36, v36, v61, s[8:9]
	v_cndmask_b32_e64 v39, v39, v44, s[8:9]
	v_cndmask_b32_e64 v36, v36, v35, s[6:7]
	v_cndmask_b32_e64 v39, v39, v38, s[6:7]
	v_cndmask_b32_e64 v35, v35, v61, s[6:7]
	v_cndmask_b32_e64 v38, v38, v44, s[6:7]
	v_cndmask_b32_e32 v35, v35, v34, vcc
	v_cndmask_b32_e32 v38, v38, v37, vcc
	v_cndmask_b32_e32 v34, v34, v61, vcc
	v_cndmask_b32_e32 v37, v37, v44, vcc
	s_cmp_le_u32 s28, 6
	s_cbranch_scc1 .Lmy_t3_done
	s_waitcnt lgkmcnt(4)
	v_mov_b32_e32 v44, 64
	v_cmp_gt_f32_e64 s[8:9], v62, v36
	v_cmp_gt_f32_e64 s[6:7], v62, v35
	v_cmp_gt_f32_e32 vcc, v62, v34
	v_cndmask_b32_e64 v36, v36, v62, s[8:9]
	v_cndmask_b32_e64 v39, v39, v44, s[8:9]
	v_cndmask_b32_e64 v36, v36, v35, s[6:7]
	v_cndmask_b32_e64 v39, v39, v38, s[6:7]
	v_cndmask_b32_e64 v35, v35, v62, s[6:7]
	v_cndmask_b32_e64 v38, v38, v44, s[6:7]
	v_cndmask_b32_e32 v35, v35, v34, vcc
	v_cndmask_b32_e32 v38, v38, v37, vcc
	v_cndmask_b32_e32 v34, v34, v62, vcc
	v_cndmask_b32_e32 v37, v37, v44, vcc
	s_cmp_le_u32 s28, 7
	s_cbranch_scc1 .Lmy_t3_done
; DEVI void moba_item(const Params& p, int l, int item) {
;     ...
;   if (tid < 128) {
;     float v1 = -INFINITY, v2 = -INFINITY, v3 = -INFINITY;
;     int i1 = -1, i2 = -1, i3 = -1;
;     for (int blk = 0; blk < qblk; ++blk) {
;       float g = gate[tid * 17 + blk];
;       if (g > v1 || i1 < 0) { v3 = v2; i3 = i2; v2 = v1; i2 = i1; v1 = g; i1 = blk; }
;       else if (g > v2 || i2 < 0) { v3 = v2; i3 = i2; v2 = g; i2 = blk; }
;       else if (g > v3 || i3 < 0) { v3 = g; i3 = blk; }
;     }
;     unsigned mask = 0u;
;     if (i1 >= 0) mask |= 1u << i1;
;     if (i2 >= 0) mask |= 1u << i2;
;     if (i3 >= 0) mask |= 1u << i3;
;     selm[tid] = mask;
;     atomicOr(&selm[128], mask);
;   }
	v_mov_b32_e32 v44, 0x80
	v_cmp_gt_f32_e64 s[8:9], v63, v36
	v_cmp_gt_f32_e64 s[6:7], v63, v35
	v_cmp_gt_f32_e32 vcc, v63, v34
	v_cndmask_b32_e64 v36, v36, v63, s[8:9]
	v_cndmask_b32_e64 v39, v39, v44, s[8:9]
	v_cndmask_b32_e64 v36, v36, v35, s[6:7]
	v_cndmask_b32_e64 v39, v39, v38, s[6:7]
	v_cndmask_b32_e64 v35, v35, v63, s[6:7]
	v_cndmask_b32_e64 v38, v38, v44, s[6:7]
	v_cndmask_b32_e32 v35, v35, v34, vcc
	v_cndmask_b32_e32 v38, v38, v37, vcc
	v_cndmask_b32_e32 v34, v34, v63, vcc
	v_cndmask_b32_e32 v37, v37, v44, vcc
	s_cmp_le_u32 s28, 8
	s_cbranch_scc1 .Lmy_t3_done
	s_waitcnt lgkmcnt(3)
	v_mov_b32_e32 v44, 0x100
	v_cmp_gt_f32_e64 s[8:9], v64, v36
	v_cmp_gt_f32_e64 s[6:7], v64, v35
	v_cmp_gt_f32_e32 vcc, v64, v34
	v_cndmask_b32_e64 v36, v36, v64, s[8:9]
	v_cndmask_b32_e64 v39, v39, v44, s[8:9]
	v_cndmask_b32_e64 v36, v36, v35, s[6:7]
	v_cndmask_b32_e64 v39, v39, v38, s[6:7]
	v_cndmask_b32_e64 v35, v35, v64, s[6:7]
	v_cndmask_b32_e64 v38, v38, v44, s[6:7]
	v_cndmask_b32_e32 v35, v35, v34, vcc
	v_cndmask_b32_e32 v38, v38, v37, vcc
	v_cndmask_b32_e32 v34, v34, v64, vcc
	v_cndmask_b32_e32 v37, v37, v44, vcc
	s_cmp_le_u32 s28, 9
	s_cbranch_scc1 .Lmy_t3_done
	v_mov_b32_e32 v44, 0x200
	v_cmp_gt_f32_e64 s[8:9], v65, v36
	v_cmp_gt_f32_e64 s[6:7], v65, v35
	v_cmp_gt_f32_e32 vcc, v65, v34
	v_cndmask_b32_e64 v36, v36, v65, s[8:9]
	v_cndmask_b32_e64 v39, v39, v44, s[8:9]
	v_cndmask_b32_e64 v36, v36, v35, s[6:7]
	v_cndmask_b32_e64 v39, v39, v38, s[6:7]
	v_cndmask_b32_e64 v35, v35, v65, s[6:7]
	v_cndmask_b32_e64 v38, v38, v44, s[6:7]
	v_cndmask_b32_e32 v35, v35, v34, vcc
	v_cndmask_b32_e32 v38, v38, v37, vcc
	v_cndmask_b32_e32 v34, v34, v65, vcc
	v_cndmask_b32_e32 v37, v37, v44, vcc
	s_cmp_le_u32 s28, 10
	s_cbranch_scc1 .Lmy_t3_done
	s_waitcnt lgkmcnt(2)
	v_mov_b32_e32 v44, 0x400
	v_cmp_gt_f32_e64 s[8:9], v66, v36
	v_cmp_gt_f32_e64 s[6:7], v66, v35
	v_cmp_gt_f32_e32 vcc, v66, v34
	v_cndmask_b32_e64 v36, v36, v66, s[8:9]
	v_cndmask_b32_e64 v39, v39, v44, s[8:9]
	v_cndmask_b32_e64 v36, v36, v35, s[6:7]
	v_cndmask_b32_e64 v39, v39, v38, s[6:7]
	v_cndmask_b32_e64 v35, v35, v66, s[6:7]
	v_cndmask_b32_e64 v38, v38, v44, s[6:7]
	v_cndmask_b32_e32 v35, v35, v34, vcc
	v_cndmask_b32_e32 v38, v38, v37, vcc
	v_cndmask_b32_e32 v34, v34, v66, vcc
	v_cndmask_b32_e32 v37, v37, v44, vcc
	s_cmp_le_u32 s28, 11
	s_cbranch_scc1 .Lmy_t3_done
	v_mov_b32_e32 v44, 0x800
	v_cmp_gt_f32_e64 s[8:9], v67, v36
	v_cmp_gt_f32_e64 s[6:7], v67, v35
	v_cmp_gt_f32_e32 vcc, v67, v34
	v_cndmask_b32_e64 v36, v36, v67, s[8:9]
	v_cndmask_b32_e64 v39, v39, v44, s[8:9]
	v_cndmask_b32_e64 v36, v36, v35, s[6:7]
	v_cndmask_b32_e64 v39, v39, v38, s[6:7]
	v_cndmask_b32_e64 v35, v35, v67, s[6:7]
	v_cndmask_b32_e64 v38, v38, v44, s[6:7]
	v_cndmask_b32_e32 v35, v35, v34, vcc
	v_cndmask_b32_e32 v38, v38, v37, vcc
	v_cndmask_b32_e32 v34, v34, v67, vcc
	v_cndmask_b32_e32 v37, v37, v44, vcc
	s_cmp_le_u32 s28, 12
	s_cbranch_scc1 .Lmy_t3_done
	s_waitcnt lgkmcnt(1)
	v_mov_b32_e32 v44, 0x1000
	v_cmp_gt_f32_e64 s[8:9], v68, v36
	v_cmp_gt_f32_e64 s[6:7], v68, v35
	v_cmp_gt_f32_e32 vcc, v68, v34
	v_cndmask_b32_e64 v36, v36, v68, s[8:9]
	v_cndmask_b32_e64 v39, v39, v44, s[8:9]
	v_cndmask_b32_e64 v36, v36, v35, s[6:7]
	v_cndmask_b32_e64 v39, v39, v38, s[6:7]
	v_cndmask_b32_e64 v35, v35, v68, s[6:7]
	v_cndmask_b32_e64 v38, v38, v44, s[6:7]
	v_cndmask_b32_e32 v35, v35, v34, vcc
	v_cndmask_b32_e32 v38, v38, v37, vcc
	v_cndmask_b32_e32 v34, v34, v68, vcc
	v_cndmask_b32_e32 v37, v37, v44, vcc
	s_cmp_le_u32 s28, 13
	s_cbranch_scc1 .Lmy_t3_done
	v_mov_b32_e32 v44, 0x2000
	v_cmp_gt_f32_e64 s[8:9], v69, v36
	v_cmp_gt_f32_e64 s[6:7], v69, v35
	v_cmp_gt_f32_e32 vcc, v69, v34
	v_cndmask_b32_e64 v36, v36, v69, s[8:9]
	v_cndmask_b32_e64 v39, v39, v44, s[8:9]
	v_cndmask_b32_e64 v36, v36, v35, s[6:7]
	v_cndmask_b32_e64 v39, v39, v38, s[6:7]
	v_cndmask_b32_e64 v35, v35, v69, s[6:7]
	v_cndmask_b32_e64 v38, v38, v44, s[6:7]
	v_cndmask_b32_e32 v35, v35, v34, vcc
	v_cndmask_b32_e32 v38, v38, v37, vcc
	v_cndmask_b32_e32 v34, v34, v69, vcc
	v_cndmask_b32_e32 v37, v37, v44, vcc
	s_cmp_le_u32 s28, 14
	s_cbranch_scc1 .Lmy_t3_done
	s_waitcnt lgkmcnt(0)
	v_mov_b32_e32 v44, 0x4000
	v_cmp_gt_f32_e64 s[8:9], v70, v36
	v_cmp_gt_f32_e64 s[6:7], v70, v35
	v_cmp_gt_f32_e32 vcc, v70, v34
	v_cndmask_b32_e64 v36, v36, v70, s[8:9]
	v_cndmask_b32_e64 v39, v39, v44, s[8:9]
	v_cndmask_b32_e64 v36, v36, v35, s[6:7]
	v_cndmask_b32_e64 v39, v39, v38, s[6:7]
	v_cndmask_b32_e64 v35, v35, v70, s[6:7]
	v_cndmask_b32_e64 v38, v38, v44, s[6:7]
	v_cndmask_b32_e32 v35, v35, v34, vcc
	v_cndmask_b32_e32 v38, v38, v37, vcc
	v_cndmask_b32_e32 v34, v34, v70, vcc
	v_cndmask_b32_e32 v37, v37, v44, vcc
.Lmy_t3_done:
	s_mov_b32 s8, 0
	s_mov_b64 s[6:7], exec
	v_or3_b32 v32, v37, v38, v39
	v_lshl_add_u32 v33, v48, 2, 0
	v_add_u32_e32 v33, 0x1e200, v33
	ds_write_b32 v33, v32
	v_mov_b32_e32 v45, s73
	ds_or_b32 v45, v32
